# rwkv_pre_wave LDS image of the chunk rows: 13-iteration load/wait/ds_write loop unrolled, all 13 loads in flight before one wait (was 13 serialized trips per item)
# speedup vs baseline: 1.0013x; 1.0013x over previous
.LBB0_928:
	s_waitcnt vmcnt(9)
	v_add_f32_e32 v61, v61, v83
	v_mul_f32_e32 v61, 0xbfb8aa3b, v61
	v_exp_f32_e32 v61, v61
	v_add_f32_e32 v58, v58, v83
	v_mul_f32_e32 v58, 0xbfb8aa3b, v58
	v_exp_f32_e32 v58, v58
	v_add_f32_e32 v61, 1.0, v61
	v_rcp_f32_e32 v61, v61
	v_add_f32_e32 v59, v59, v83
	v_add_f32_e32 v57, v57, v83
	v_add_f32_e32 v50, v50, v83
	v_add_f32_e32 v51, v51, v83
	v_mul_f32_e32 v59, 0xbfb8aa3b, v59
	v_add_f32_e32 v58, 1.0, v58
	v_mul_f32_e32 v57, 0xbfb8aa3b, v57
	v_mul_f32_e32 v50, 0xbfb8aa3b, v50
	v_mul_f32_e32 v51, 0xbfb8aa3b, v51
	v_add_f32_e32 v60, v60, v83
	v_mul_f32_e32 v64, 0xbf1b459e, v61
	v_exp_f32_e32 v59, v59
	v_rcp_f32_e32 v58, v58
	v_exp_f32_e32 v61, v57
	v_add_f32_e32 v48, v48, v83
	v_add_f32_e32 v49, v49, v83
	v_exp_f32_e32 v50, v50
	v_exp_f32_e32 v51, v51
	v_mul_f32_e32 v60, 0xbfb8aa3b, v60
	v_mul_f32_e32 v48, 0xbfb8aa3b, v48
	v_mul_f32_e32 v49, 0xbfb8aa3b, v49
	v_exp_f32_e32 v60, v60
	v_exp_f32_e32 v48, v48
	v_exp_f32_e32 v49, v49
	v_add_f32_e32 v59, 1.0, v59
	v_mul_f32_e32 v66, 0xbf1b459e, v58
	v_add_f32_e32 v58, 1.0, v61
	v_add_f32_e32 v50, 1.0, v50
	v_add_f32_e32 v51, 1.0, v51
	v_rcp_f32_e32 v59, v59
	v_rcp_f32_e32 v58, v58
	v_rcp_f32_e32 v50, v50
	v_rcp_f32_e32 v51, v51
	v_add_f32_e32 v60, 1.0, v60
	v_add_f32_e32 v48, 1.0, v48
	v_add_f32_e32 v49, 1.0, v49
	v_rcp_f32_e32 v60, v60
	v_rcp_f32_e32 v48, v48
	v_rcp_f32_e32 v49, v49
	v_add_f32_e32 v52, v52, v83
	v_mul_f32_e32 v52, 0xbfb8aa3b, v52
	s_mov_b32 s4, 0xbf1b459e
	v_mul_f32_e32 v65, 0xbf1b459e, v59
	v_exp_f32_e32 v67, v52
	v_mul_f32_e32 v52, 0xbf1b459e, v58
	v_pk_mul_f32 v[58:59], v[50:51], s[4:5] op_sel_hi:[1,0]
	v_add_f32_e32 v50, v54, v83
	v_mul_f32_e32 v50, 0xbfb8aa3b, v50
	v_add_f32_e32 v51, v55, v83
	v_add_f32_e32 v32, v32, v96
	v_add_f32_e32 v33, v33, v96
	v_add_f32_e32 v34, v34, v96
	v_add_f32_e32 v35, v35, v96
	v_mul_f32_e32 v57, 0xbf1b459e, v60
	v_pk_mul_f32 v[60:61], v[48:49], s[4:5] op_sel_hi:[1,0]
	v_add_f32_e32 v49, v53, v83
	v_exp_f32_e32 v50, v50
	v_mul_f32_e32 v51, 0xbfb8aa3b, v51
	v_add_f32_e32 v53, v56, v83
	v_mul_f32_e32 v32, 0xbfb8aa3b, v32
	v_mul_f32_e32 v33, 0xbfb8aa3b, v33
	v_mul_f32_e32 v34, 0xbfb8aa3b, v34
	v_mul_f32_e32 v35, 0xbfb8aa3b, v35
	v_add_f32_e32 v36, v36, v96
	v_add_f32_e32 v37, v37, v96
	v_exp_f32_e32 v51, v51
	v_mul_f32_e32 v53, 0xbfb8aa3b, v53
	v_exp_f32_e32 v32, v32
	v_exp_f32_e32 v33, v33
	v_exp_f32_e32 v34, v34
	v_exp_f32_e32 v35, v35
	v_mul_f32_e32 v36, 0xbfb8aa3b, v36
	v_mul_f32_e32 v37, 0xbfb8aa3b, v37
	v_mul_f32_e32 v49, 0xbfb8aa3b, v49
	v_exp_f32_e32 v53, v53
	v_exp_f32_e32 v36, v36
	v_exp_f32_e32 v37, v37
	v_exp_f32_e32 v49, v49
	v_add_f32_e32 v50, 1.0, v50
	v_rcp_f32_e32 v54, v50
	v_add_f32_e32 v50, 1.0, v51
	v_add_f32_e32 v47, v47, v96
	v_add_f32_e32 v32, 1.0, v32
	v_add_f32_e32 v33, 1.0, v33
	v_add_f32_e32 v34, 1.0, v34
	v_add_f32_e32 v35, 1.0, v35
	v_rcp_f32_e32 v55, v50
	v_add_f32_e32 v50, 1.0, v53
	v_mul_f32_e32 v47, 0xbfb8aa3b, v47
	v_add_f32_e32 v46, v46, v96
	v_add_f32_e32 v45, v45, v96
	v_rcp_f32_e32 v32, v32
	v_rcp_f32_e32 v33, v33
	v_rcp_f32_e32 v34, v34
	v_rcp_f32_e32 v35, v35
	v_add_f32_e32 v36, 1.0, v36
	v_add_f32_e32 v37, 1.0, v37
	v_add_f32_e32 v48, 1.0, v67
	v_add_f32_e32 v49, 1.0, v49
	v_rcp_f32_e32 v53, v50
	v_exp_f32_e32 v56, v47
	v_mul_f32_e32 v46, 0xbfb8aa3b, v46
	v_mul_f32_e32 v45, 0xbfb8aa3b, v45
	v_rcp_f32_e32 v36, v36
	v_rcp_f32_e32 v37, v37
	v_rcp_f32_e32 v48, v48
	v_rcp_f32_e32 v49, v49
	v_exp_f32_e32 v46, v46
	v_exp_f32_e32 v45, v45
	v_add_f32_e32 v44, v44, v96
	v_add_f32_e32 v43, v43, v96
	v_add_f32_e32 v42, v42, v96
	v_add_f32_e32 v41, v41, v96
	v_add_f32_e32 v38, v38, v96
	v_pk_mul_f32 v[92:93], v[32:33], s[4:5] op_sel_hi:[1,0]
	v_pk_mul_f32 v[86:87], v[34:35], s[4:5] op_sel_hi:[1,0]
	v_add_f32_e32 v33, v39, v96
	v_add_f32_e32 v34, v40, v96
	v_add_f32_e32 v35, v62, v83
	v_mul_f32_e32 v47, 0xbf1b459e, v53
	v_add_f32_e32 v53, 1.0, v56
	v_mul_f32_e32 v44, 0xbfb8aa3b, v44
	v_mul_f32_e32 v43, 0xbfb8aa3b, v43
	v_mul_f32_e32 v42, 0xbfb8aa3b, v42
	v_mul_f32_e32 v41, 0xbfb8aa3b, v41
	v_mul_f32_e32 v38, 0xbfb8aa3b, v38
	v_pk_mul_f32 v[80:81], v[36:37], s[4:5] op_sel_hi:[1,0]
	v_mul_f32_e32 v33, 0xbfb8aa3b, v33
	v_mul_f32_e32 v34, 0xbfb8aa3b, v34
	v_mul_f32_e32 v35, 0xbfb8aa3b, v35
	v_add_f32_e32 v36, v63, v83
	v_pk_mul_f32 v[50:51], v[48:49], s[4:5] op_sel_hi:[1,0]
	v_pk_mul_f32 v[48:49], v[54:55], s[4:5] op_sel_hi:[1,0]
	v_rcp_f32_e32 v53, v53
	v_add_f32_e32 v46, 1.0, v46
	v_add_f32_e32 v45, 1.0, v45
	v_exp_f32_e32 v55, v44
	v_exp_f32_e32 v43, v43
	v_exp_f32_e32 v42, v42
	v_exp_f32_e32 v41, v41
	v_exp_f32_e32 v38, v38
	v_exp_f32_e32 v33, v33
	v_exp_f32_e32 v34, v34
	v_exp_f32_e32 v35, v35
	v_mul_f32_e32 v36, 0xbfb8aa3b, v36
	v_rcp_f32_e32 v46, v46
	v_rcp_f32_e32 v54, v45
	v_exp_f32_e32 v36, v36
	v_mul_f32_e32 v44, 0xbf1b459e, v53
	v_add_f32_e32 v53, 1.0, v55
	v_add_f32_e32 v43, 1.0, v43
	v_add_f32_e32 v42, 1.0, v42
	v_add_f32_e32 v41, 1.0, v41
	v_add_f32_e32 v32, 1.0, v38
	v_add_f32_e32 v33, 1.0, v33
	v_add_f32_e32 v34, 1.0, v34
	v_add_f32_e32 v35, 1.0, v35
	v_mul_f32_e32 v45, 0xbf1b459e, v46
	v_mul_f32_e32 v46, 0xbf1b459e, v54
	v_rcp_f32_e32 v53, v53
	v_rcp_f32_e32 v43, v43
	v_rcp_f32_e32 v54, v42
	v_rcp_f32_e32 v41, v41
	v_rcp_f32_e32 v32, v32
	v_rcp_f32_e32 v33, v33
	v_rcp_f32_e32 v34, v34
	v_rcp_f32_e32 v35, v35
	v_add_f32_e32 v36, 1.0, v36
	v_rcp_f32_e32 v36, v36
	v_mul_f32_e32 v42, 0xbf1b459e, v53
	v_mul_f32_e32 v43, 0xbf1b459e, v43
	v_mul_f32_e32 v53, 0xbf1b459e, v54
	v_mul_f32_e32 v56, 0xbf1b459e, v41
	v_pk_mul_f32 v[74:75], v[32:33], s[4:5] op_sel_hi:[1,0]
	v_mul_f32_e32 v62, 0xbf1b459e, v34
	v_mul_f32_e32 v63, 0xbf1b459e, v35
	v_mul_f32_e32 v32, 0xbf1b459e, v36
	v_add_f32_e32 v34, 0, v92
	v_add_f32_e32 v34, v93, v34
	v_add_f32_e32 v34, v86, v34
	v_add_f32_e32 v91, v87, v34
	v_add_f32_e32 v34, 0, v80
	v_add_f32_e32 v34, v81, v34
	v_add_f32_e32 v34, v74, v34
	v_cndmask_b32_e64 v68, 0, v62, s[0:1]
	v_add_f32_e32 v110, v75, v34
	v_add_f32_e32 v34, 0, v68
	v_cndmask_b32_e64 v69, 0, v56, s[0:1]
	v_add_f32_e32 v34, v34, v69
	v_cndmask_b32_e64 v70, 0, v53, s[0:1]
	v_add_f32_e32 v34, v34, v70
	v_cndmask_b32_e64 v71, 0, v43, s[0:1]
	v_cndmask_b32_e64 v72, 0, v42, s[0:1]
	v_add_f32_e32 v113, v34, v71
	v_add_f32_e32 v34, 0, v72
	v_cndmask_b32_e64 v73, 0, v46, s[0:1]
	v_add_f32_e32 v34, v34, v73
	v_cndmask_b32_e64 v76, 0, v45, s[0:1]
	v_add_f32_e32 v34, v34, v76
	v_cndmask_b32_e64 v77, 0, v44, s[0:1]
	v_add_f32_e32 v159, v34, v77
	v_add_f32_e32 v34, 0, v60
	v_add_f32_e32 v34, v61, v34
	v_add_f32_e32 v34, v58, v34
	v_add_f32_e32 v37, v59, v34
	v_add_f32_e32 v34, 0, v50
	v_add_f32_e32 v34, v51, v34
	v_add_f32_e32 v34, v48, v34
	v_cndmask_b32_e64 v78, 0, v47, s[0:1]
	v_add_f32_e32 v129, v49, v34
	v_add_f32_e32 v34, 0, v78
	v_cndmask_b32_e64 v79, 0, v52, s[0:1]
	v_add_f32_e32 v34, v34, v79
	v_cndmask_b32_e64 v83, 0, v66, s[0:1]
	v_add_f32_e32 v34, v34, v83
	v_cndmask_b32_e64 v85, 0, v65, s[0:1]
	v_cndmask_b32_e64 v67, 0, v57, s[0:1]
	v_add_f32_e32 v131, v34, v85
	v_add_f32_e32 v34, 0, v67
	v_cndmask_b32_e64 v88, 0, v64, s[0:1]
	v_cmp_lt_i32_e32 vcc, v218, v252
	v_add_f32_e32 v34, v34, v88
	v_cndmask_b32_e64 v89, 0, v63, s[0:1]
	v_cndmask_b32_e32 v33, v217, v218, vcc
	v_add_f32_e32 v34, v34, v89
	v_cndmask_b32_e64 v39, 0, v32, s[0:1]
	v_lshlrev_b32_e32 v33, 2, v33
	v_add_f32_e32 v133, v34, v39
	ds_bpermute_b32 v95, v33, v91
	ds_bpermute_b32 v111, v33, v110
	ds_bpermute_b32 v158, v33, v113
	ds_bpermute_b32 v160, v33, v159
	ds_bpermute_b32 v128, v33, v37
	ds_bpermute_b32 v130, v33, v129
	ds_bpermute_b32 v132, v33, v131
	ds_bpermute_b32 v134, v33, v133
	s_movk_i32 s4, 0x318
	v_cmp_gt_i32_e32 vcc, s4, v136
	s_and_saveexec_b64 s[4:5], vcc
	s_cbranch_execz .LBB0_935
	s_add_i32 s15, s10, -1
	v_lshlrev_b32_e32 v36, 3, v136
	v_lshlrev_b32_e32 v38, 6, v136
	s_mov_b64 s[8:9], 0
	v_mov_b32_e32 v54, v136
	s_mov_b32 s10, 0x2aaaaaab
	v_mul_hi_i32 v32, v54, s10
	v_lshrrev_b32_e32 v33, 31, v32
	v_ashrrev_i32_e32 v32, 2, v32
	v_add_u32_e32 v55, v32, v33
	v_add_u32_e32 v96, s15, v55
	s_movk_i32 s10, 0x80f
	v_cmp_lt_u32_e32 vcc, s10, v96
	s_and_saveexec_b64 s[10:11], vcc
	s_xor_b64 s[10:11], exec, s[10:11]
	s_movk_i32 s16, 0xff40
	v_mad_u64_u32 v[40:41], s[16:17], v55, s16, v[36:37]
	v_and_b32_e32 v41, 56, v40
	s_or_saveexec_b64 s[10:11], s[10:11]
	v_mov_b32_e32 v162, 0
	v_mov_b32_e32 v163, 0
	v_mov_b32_e32 v164, 0
	v_mov_b32_e32 v165, 0
	s_xor_b64 exec, exec, s[10:11]
	v_lshl_add_u64 v[32:33], s[6:7], 0, v[96:97]
	v_mov_b64_e32 v[34:35], s[56:57]
	v_mad_u64_u32 v[34:35], s[16:17], v32, s44, v[34:35]
	v_mov_b32_e32 v32, v35
	v_mad_u64_u32 v[32:33], s[16:17], v33, s44, v[32:33]
	s_movk_i32 s16, 0xfa00
	v_mov_b32_e32 v35, v32
	v_mad_u64_u32 v[32:33], s[16:17], v55, s16, v[38:39]
	v_and_b32_e32 v32, 0xfffffe00, v32
	s_movk_i32 s16, 0xff40
	v_ashrrev_i32_e32 v33, 31, v32
	v_mad_u64_u32 v[40:41], s[16:17], v55, s16, v[36:37]
	v_lshl_add_u64 v[32:33], v[32:33], 1, v[34:35]
	v_and_b32_e32 v41, 56, v40
	v_lshl_add_u64 v[32:33], v[32:33], 0, s[38:39]
	v_lshlrev_b32_e32 v96, 1, v41
	v_lshl_add_u64 v[32:33], v[32:33], 0, v[96:97]
	global_load_dwordx4 v[162:165], v[32:33], off
	s_or_b64 exec, exec, s[10:11]
	s_movk_i32 s10, 0x190
	v_mul_lo_u32 v55, v55, s10
	v_and_b32_e32 v40, 0x7fffffc0, v40
	v_add_u32_e32 v55, s76, v55
	v_lshlrev_b32_e32 v40, 1, v40
	v_lshlrev_b32_e32 v41, 1, v41
	v_add3_u32 v139, v55, v40, v41
	s_movk_i32 s10, 0x2d7
	s_mov_b64 s[98:99], exec
	v_add_u32_e32 v32, 64, v54
	v_cmp_lt_i32_e32 vcc, s10, v54
	v_add_u32_e32 v36, 0x200, v36
	v_add_u32_e32 v38, 0x1000, v38
	s_or_b64 s[8:9], vcc, s[8:9]
	v_mov_b32_e32 v54, v32
	s_andn2_b64 exec, exec, s[8:9]
	s_mov_b32 s10, 0x2aaaaaab
	v_mul_hi_i32 v32, v54, s10
	v_lshrrev_b32_e32 v33, 31, v32
	v_ashrrev_i32_e32 v32, 2, v32
	v_add_u32_e32 v55, v32, v33
	v_add_u32_e32 v96, s15, v55
	s_movk_i32 s10, 0x80f
	v_cmp_lt_u32_e32 vcc, s10, v96
	s_and_saveexec_b64 s[10:11], vcc
	s_xor_b64 s[10:11], exec, s[10:11]
	s_movk_i32 s16, 0xff40
	v_mad_u64_u32 v[40:41], s[16:17], v55, s16, v[36:37]
	v_and_b32_e32 v41, 56, v40
	s_or_saveexec_b64 s[10:11], s[10:11]
	v_mov_b32_e32 v166, 0
	v_mov_b32_e32 v167, 0
	v_mov_b32_e32 v168, 0
	v_mov_b32_e32 v169, 0
	s_xor_b64 exec, exec, s[10:11]
	v_lshl_add_u64 v[32:33], s[6:7], 0, v[96:97]
	v_mov_b64_e32 v[34:35], s[56:57]
	v_mad_u64_u32 v[34:35], s[16:17], v32, s44, v[34:35]
	v_mov_b32_e32 v32, v35
	v_mad_u64_u32 v[32:33], s[16:17], v33, s44, v[32:33]
	s_movk_i32 s16, 0xfa00
	v_mov_b32_e32 v35, v32
	v_mad_u64_u32 v[32:33], s[16:17], v55, s16, v[38:39]
	v_and_b32_e32 v32, 0xfffffe00, v32
	s_movk_i32 s16, 0xff40
	v_ashrrev_i32_e32 v33, 31, v32
	v_mad_u64_u32 v[40:41], s[16:17], v55, s16, v[36:37]
	v_lshl_add_u64 v[32:33], v[32:33], 1, v[34:35]
	v_and_b32_e32 v41, 56, v40
	v_lshl_add_u64 v[32:33], v[32:33], 0, s[38:39]
	v_lshlrev_b32_e32 v96, 1, v41
	v_lshl_add_u64 v[32:33], v[32:33], 0, v[96:97]
	global_load_dwordx4 v[166:169], v[32:33], off
	s_or_b64 exec, exec, s[10:11]
	s_movk_i32 s10, 0x190
	v_mul_lo_u32 v55, v55, s10
	v_and_b32_e32 v40, 0x7fffffc0, v40
	v_add_u32_e32 v55, s76, v55
	v_lshlrev_b32_e32 v40, 1, v40
	v_lshlrev_b32_e32 v41, 1, v41
	v_add3_u32 v140, v55, v40, v41
	s_movk_i32 s10, 0x2d7
	v_add_u32_e32 v32, 64, v54
	v_cmp_lt_i32_e32 vcc, s10, v54
	v_add_u32_e32 v36, 0x200, v36
	v_add_u32_e32 v38, 0x1000, v38
	s_or_b64 s[8:9], vcc, s[8:9]
	v_mov_b32_e32 v54, v32
	s_andn2_b64 exec, exec, s[8:9]
	s_mov_b32 s10, 0x2aaaaaab
	v_mul_hi_i32 v32, v54, s10
	v_lshrrev_b32_e32 v33, 31, v32
	v_ashrrev_i32_e32 v32, 2, v32
	v_add_u32_e32 v55, v32, v33
	v_add_u32_e32 v96, s15, v55
	s_movk_i32 s10, 0x80f
	v_cmp_lt_u32_e32 vcc, s10, v96
	s_and_saveexec_b64 s[10:11], vcc
	s_xor_b64 s[10:11], exec, s[10:11]
	s_movk_i32 s16, 0xff40
	v_mad_u64_u32 v[40:41], s[16:17], v55, s16, v[36:37]
	v_and_b32_e32 v41, 56, v40
	s_or_saveexec_b64 s[10:11], s[10:11]
	v_mov_b32_e32 v170, 0
	v_mov_b32_e32 v171, 0
	v_mov_b32_e32 v172, 0
	v_mov_b32_e32 v173, 0
	s_xor_b64 exec, exec, s[10:11]
	v_lshl_add_u64 v[32:33], s[6:7], 0, v[96:97]
	v_mov_b64_e32 v[34:35], s[56:57]
	v_mad_u64_u32 v[34:35], s[16:17], v32, s44, v[34:35]
	v_mov_b32_e32 v32, v35
	v_mad_u64_u32 v[32:33], s[16:17], v33, s44, v[32:33]
	s_movk_i32 s16, 0xfa00
	v_mov_b32_e32 v35, v32
	v_mad_u64_u32 v[32:33], s[16:17], v55, s16, v[38:39]
	v_and_b32_e32 v32, 0xfffffe00, v32
	s_movk_i32 s16, 0xff40
	v_ashrrev_i32_e32 v33, 31, v32
	v_mad_u64_u32 v[40:41], s[16:17], v55, s16, v[36:37]
	v_lshl_add_u64 v[32:33], v[32:33], 1, v[34:35]
	v_and_b32_e32 v41, 56, v40
	v_lshl_add_u64 v[32:33], v[32:33], 0, s[38:39]
	v_lshlrev_b32_e32 v96, 1, v41
	v_lshl_add_u64 v[32:33], v[32:33], 0, v[96:97]
	global_load_dwordx4 v[170:173], v[32:33], off
	s_or_b64 exec, exec, s[10:11]
	s_movk_i32 s10, 0x190
	v_mul_lo_u32 v55, v55, s10
	v_and_b32_e32 v40, 0x7fffffc0, v40
	v_add_u32_e32 v55, s76, v55
	v_lshlrev_b32_e32 v40, 1, v40
	v_lshlrev_b32_e32 v41, 1, v41
	v_add3_u32 v141, v55, v40, v41
	s_movk_i32 s10, 0x2d7
	v_add_u32_e32 v32, 64, v54
	v_cmp_lt_i32_e32 vcc, s10, v54
	v_add_u32_e32 v36, 0x200, v36
	v_add_u32_e32 v38, 0x1000, v38
	s_or_b64 s[8:9], vcc, s[8:9]
	v_mov_b32_e32 v54, v32
	s_andn2_b64 exec, exec, s[8:9]
	s_mov_b32 s10, 0x2aaaaaab
	v_mul_hi_i32 v32, v54, s10
	v_lshrrev_b32_e32 v33, 31, v32
	v_ashrrev_i32_e32 v32, 2, v32
	v_add_u32_e32 v55, v32, v33
	v_add_u32_e32 v96, s15, v55
	s_movk_i32 s10, 0x80f
	v_cmp_lt_u32_e32 vcc, s10, v96
	s_and_saveexec_b64 s[10:11], vcc
	s_xor_b64 s[10:11], exec, s[10:11]
	s_movk_i32 s16, 0xff40
	v_mad_u64_u32 v[40:41], s[16:17], v55, s16, v[36:37]
	v_and_b32_e32 v41, 56, v40
	s_or_saveexec_b64 s[10:11], s[10:11]
	v_mov_b32_e32 v174, 0
	v_mov_b32_e32 v175, 0
	v_mov_b32_e32 v176, 0
	v_mov_b32_e32 v177, 0
	s_xor_b64 exec, exec, s[10:11]
	v_lshl_add_u64 v[32:33], s[6:7], 0, v[96:97]
	v_mov_b64_e32 v[34:35], s[56:57]
	v_mad_u64_u32 v[34:35], s[16:17], v32, s44, v[34:35]
	v_mov_b32_e32 v32, v35
	v_mad_u64_u32 v[32:33], s[16:17], v33, s44, v[32:33]
	s_movk_i32 s16, 0xfa00
	v_mov_b32_e32 v35, v32
	v_mad_u64_u32 v[32:33], s[16:17], v55, s16, v[38:39]
	v_and_b32_e32 v32, 0xfffffe00, v32
	s_movk_i32 s16, 0xff40
	v_ashrrev_i32_e32 v33, 31, v32
	v_mad_u64_u32 v[40:41], s[16:17], v55, s16, v[36:37]
	v_lshl_add_u64 v[32:33], v[32:33], 1, v[34:35]
	v_and_b32_e32 v41, 56, v40
	v_lshl_add_u64 v[32:33], v[32:33], 0, s[38:39]
	v_lshlrev_b32_e32 v96, 1, v41
	v_lshl_add_u64 v[32:33], v[32:33], 0, v[96:97]
	global_load_dwordx4 v[174:177], v[32:33], off
	s_or_b64 exec, exec, s[10:11]
	s_movk_i32 s10, 0x190
	v_mul_lo_u32 v55, v55, s10
	v_and_b32_e32 v40, 0x7fffffc0, v40
	v_add_u32_e32 v55, s76, v55
	v_lshlrev_b32_e32 v40, 1, v40
	v_lshlrev_b32_e32 v41, 1, v41
	v_add3_u32 v142, v55, v40, v41
	s_movk_i32 s10, 0x2d7
	v_add_u32_e32 v32, 64, v54
	v_cmp_lt_i32_e32 vcc, s10, v54
	v_add_u32_e32 v36, 0x200, v36
	v_add_u32_e32 v38, 0x1000, v38
	s_or_b64 s[8:9], vcc, s[8:9]
	v_mov_b32_e32 v54, v32
	s_andn2_b64 exec, exec, s[8:9]
	s_mov_b32 s10, 0x2aaaaaab
	v_mul_hi_i32 v32, v54, s10
	v_lshrrev_b32_e32 v33, 31, v32
	v_ashrrev_i32_e32 v32, 2, v32
	v_add_u32_e32 v55, v32, v33
	v_add_u32_e32 v96, s15, v55
	s_movk_i32 s10, 0x80f
	v_cmp_lt_u32_e32 vcc, s10, v96
	s_and_saveexec_b64 s[10:11], vcc
	s_xor_b64 s[10:11], exec, s[10:11]
	s_movk_i32 s16, 0xff40
	v_mad_u64_u32 v[40:41], s[16:17], v55, s16, v[36:37]
	v_and_b32_e32 v41, 56, v40
	s_or_saveexec_b64 s[10:11], s[10:11]
	v_mov_b32_e32 v178, 0
	v_mov_b32_e32 v179, 0
	v_mov_b32_e32 v180, 0
	v_mov_b32_e32 v181, 0
	s_xor_b64 exec, exec, s[10:11]
	v_lshl_add_u64 v[32:33], s[6:7], 0, v[96:97]
	v_mov_b64_e32 v[34:35], s[56:57]
	v_mad_u64_u32 v[34:35], s[16:17], v32, s44, v[34:35]
	v_mov_b32_e32 v32, v35
	v_mad_u64_u32 v[32:33], s[16:17], v33, s44, v[32:33]
	s_movk_i32 s16, 0xfa00
	v_mov_b32_e32 v35, v32
	v_mad_u64_u32 v[32:33], s[16:17], v55, s16, v[38:39]
	v_and_b32_e32 v32, 0xfffffe00, v32
	s_movk_i32 s16, 0xff40
	v_ashrrev_i32_e32 v33, 31, v32
	v_mad_u64_u32 v[40:41], s[16:17], v55, s16, v[36:37]
	v_lshl_add_u64 v[32:33], v[32:33], 1, v[34:35]
	v_and_b32_e32 v41, 56, v40
	v_lshl_add_u64 v[32:33], v[32:33], 0, s[38:39]
	v_lshlrev_b32_e32 v96, 1, v41
	v_lshl_add_u64 v[32:33], v[32:33], 0, v[96:97]
	global_load_dwordx4 v[178:181], v[32:33], off
	s_or_b64 exec, exec, s[10:11]
	s_movk_i32 s10, 0x190
	v_mul_lo_u32 v55, v55, s10
	v_and_b32_e32 v40, 0x7fffffc0, v40
	v_add_u32_e32 v55, s76, v55
	v_lshlrev_b32_e32 v40, 1, v40
	v_lshlrev_b32_e32 v41, 1, v41
	v_add3_u32 v143, v55, v40, v41
	s_movk_i32 s10, 0x2d7
	v_add_u32_e32 v32, 64, v54
	v_cmp_lt_i32_e32 vcc, s10, v54
	v_add_u32_e32 v36, 0x200, v36
	v_add_u32_e32 v38, 0x1000, v38
	s_or_b64 s[8:9], vcc, s[8:9]
	v_mov_b32_e32 v54, v32
	s_andn2_b64 exec, exec, s[8:9]
	s_mov_b32 s10, 0x2aaaaaab
	v_mul_hi_i32 v32, v54, s10
	v_lshrrev_b32_e32 v33, 31, v32
	v_ashrrev_i32_e32 v32, 2, v32
	v_add_u32_e32 v55, v32, v33
	v_add_u32_e32 v96, s15, v55
	s_movk_i32 s10, 0x80f
	v_cmp_lt_u32_e32 vcc, s10, v96
	s_and_saveexec_b64 s[10:11], vcc
	s_xor_b64 s[10:11], exec, s[10:11]
	s_movk_i32 s16, 0xff40
	v_mad_u64_u32 v[40:41], s[16:17], v55, s16, v[36:37]
	v_and_b32_e32 v41, 56, v40
	s_or_saveexec_b64 s[10:11], s[10:11]
	v_mov_b32_e32 v182, 0
	v_mov_b32_e32 v183, 0
	v_mov_b32_e32 v184, 0
	v_mov_b32_e32 v185, 0
	s_xor_b64 exec, exec, s[10:11]
	v_lshl_add_u64 v[32:33], s[6:7], 0, v[96:97]
	v_mov_b64_e32 v[34:35], s[56:57]
	v_mad_u64_u32 v[34:35], s[16:17], v32, s44, v[34:35]
	v_mov_b32_e32 v32, v35
	v_mad_u64_u32 v[32:33], s[16:17], v33, s44, v[32:33]
	s_movk_i32 s16, 0xfa00
	v_mov_b32_e32 v35, v32
	v_mad_u64_u32 v[32:33], s[16:17], v55, s16, v[38:39]
	v_and_b32_e32 v32, 0xfffffe00, v32
	s_movk_i32 s16, 0xff40
	v_ashrrev_i32_e32 v33, 31, v32
	v_mad_u64_u32 v[40:41], s[16:17], v55, s16, v[36:37]
	v_lshl_add_u64 v[32:33], v[32:33], 1, v[34:35]
	v_and_b32_e32 v41, 56, v40
	v_lshl_add_u64 v[32:33], v[32:33], 0, s[38:39]
	v_lshlrev_b32_e32 v96, 1, v41
	v_lshl_add_u64 v[32:33], v[32:33], 0, v[96:97]
	global_load_dwordx4 v[182:185], v[32:33], off
	s_or_b64 exec, exec, s[10:11]
	s_movk_i32 s10, 0x190
	v_mul_lo_u32 v55, v55, s10
	v_and_b32_e32 v40, 0x7fffffc0, v40
	v_add_u32_e32 v55, s76, v55
	v_lshlrev_b32_e32 v40, 1, v40
	v_lshlrev_b32_e32 v41, 1, v41
	v_add3_u32 v144, v55, v40, v41
	s_movk_i32 s10, 0x2d7
	v_add_u32_e32 v32, 64, v54
	v_cmp_lt_i32_e32 vcc, s10, v54
	v_add_u32_e32 v36, 0x200, v36
	v_add_u32_e32 v38, 0x1000, v38
	s_or_b64 s[8:9], vcc, s[8:9]
	v_mov_b32_e32 v54, v32
	s_andn2_b64 exec, exec, s[8:9]
	s_mov_b32 s10, 0x2aaaaaab
	v_mul_hi_i32 v32, v54, s10
	v_lshrrev_b32_e32 v33, 31, v32
	v_ashrrev_i32_e32 v32, 2, v32
	v_add_u32_e32 v55, v32, v33
	v_add_u32_e32 v96, s15, v55
	s_movk_i32 s10, 0x80f
	v_cmp_lt_u32_e32 vcc, s10, v96
	s_and_saveexec_b64 s[10:11], vcc
	s_xor_b64 s[10:11], exec, s[10:11]
	s_movk_i32 s16, 0xff40
	v_mad_u64_u32 v[40:41], s[16:17], v55, s16, v[36:37]
	v_and_b32_e32 v41, 56, v40
	s_or_saveexec_b64 s[10:11], s[10:11]
	v_mov_b32_e32 v186, 0
	v_mov_b32_e32 v187, 0
	v_mov_b32_e32 v188, 0
	v_mov_b32_e32 v189, 0
	s_xor_b64 exec, exec, s[10:11]
	v_lshl_add_u64 v[32:33], s[6:7], 0, v[96:97]
	v_mov_b64_e32 v[34:35], s[56:57]
	v_mad_u64_u32 v[34:35], s[16:17], v32, s44, v[34:35]
	v_mov_b32_e32 v32, v35
	v_mad_u64_u32 v[32:33], s[16:17], v33, s44, v[32:33]
	s_movk_i32 s16, 0xfa00
	v_mov_b32_e32 v35, v32
	v_mad_u64_u32 v[32:33], s[16:17], v55, s16, v[38:39]
	v_and_b32_e32 v32, 0xfffffe00, v32
	s_movk_i32 s16, 0xff40
	v_ashrrev_i32_e32 v33, 31, v32
	v_mad_u64_u32 v[40:41], s[16:17], v55, s16, v[36:37]
	v_lshl_add_u64 v[32:33], v[32:33], 1, v[34:35]
	v_and_b32_e32 v41, 56, v40
	v_lshl_add_u64 v[32:33], v[32:33], 0, s[38:39]
	v_lshlrev_b32_e32 v96, 1, v41
	v_lshl_add_u64 v[32:33], v[32:33], 0, v[96:97]
	global_load_dwordx4 v[186:189], v[32:33], off
	s_or_b64 exec, exec, s[10:11]
	s_movk_i32 s10, 0x190
	v_mul_lo_u32 v55, v55, s10
	v_and_b32_e32 v40, 0x7fffffc0, v40
	v_add_u32_e32 v55, s76, v55
	v_lshlrev_b32_e32 v40, 1, v40
	v_lshlrev_b32_e32 v41, 1, v41
	v_add3_u32 v145, v55, v40, v41
	s_movk_i32 s10, 0x2d7
	v_add_u32_e32 v32, 64, v54
	v_cmp_lt_i32_e32 vcc, s10, v54
	v_add_u32_e32 v36, 0x200, v36
	v_add_u32_e32 v38, 0x1000, v38
	s_or_b64 s[8:9], vcc, s[8:9]
	v_mov_b32_e32 v54, v32
	s_andn2_b64 exec, exec, s[8:9]
	s_mov_b32 s10, 0x2aaaaaab
	v_mul_hi_i32 v32, v54, s10
	v_lshrrev_b32_e32 v33, 31, v32
	v_ashrrev_i32_e32 v32, 2, v32
	v_add_u32_e32 v55, v32, v33
	v_add_u32_e32 v96, s15, v55
	s_movk_i32 s10, 0x80f
	v_cmp_lt_u32_e32 vcc, s10, v96
	s_and_saveexec_b64 s[10:11], vcc
	s_xor_b64 s[10:11], exec, s[10:11]
	s_movk_i32 s16, 0xff40
	v_mad_u64_u32 v[40:41], s[16:17], v55, s16, v[36:37]
	v_and_b32_e32 v41, 56, v40
	s_or_saveexec_b64 s[10:11], s[10:11]
	v_mov_b32_e32 v190, 0
	v_mov_b32_e32 v191, 0
	v_mov_b32_e32 v192, 0
	v_mov_b32_e32 v193, 0
	s_xor_b64 exec, exec, s[10:11]
	v_lshl_add_u64 v[32:33], s[6:7], 0, v[96:97]
	v_mov_b64_e32 v[34:35], s[56:57]
	v_mad_u64_u32 v[34:35], s[16:17], v32, s44, v[34:35]
	v_mov_b32_e32 v32, v35
	v_mad_u64_u32 v[32:33], s[16:17], v33, s44, v[32:33]
	s_movk_i32 s16, 0xfa00
	v_mov_b32_e32 v35, v32
	v_mad_u64_u32 v[32:33], s[16:17], v55, s16, v[38:39]
	v_and_b32_e32 v32, 0xfffffe00, v32
	s_movk_i32 s16, 0xff40
	v_ashrrev_i32_e32 v33, 31, v32
	v_mad_u64_u32 v[40:41], s[16:17], v55, s16, v[36:37]
	v_lshl_add_u64 v[32:33], v[32:33], 1, v[34:35]
	v_and_b32_e32 v41, 56, v40
	v_lshl_add_u64 v[32:33], v[32:33], 0, s[38:39]
	v_lshlrev_b32_e32 v96, 1, v41
	v_lshl_add_u64 v[32:33], v[32:33], 0, v[96:97]
	global_load_dwordx4 v[190:193], v[32:33], off
	s_or_b64 exec, exec, s[10:11]
	s_movk_i32 s10, 0x190
	v_mul_lo_u32 v55, v55, s10
	v_and_b32_e32 v40, 0x7fffffc0, v40
	v_add_u32_e32 v55, s76, v55
	v_lshlrev_b32_e32 v40, 1, v40
	v_lshlrev_b32_e32 v41, 1, v41
	v_add3_u32 v146, v55, v40, v41
	s_movk_i32 s10, 0x2d7
	v_add_u32_e32 v32, 64, v54
	v_cmp_lt_i32_e32 vcc, s10, v54
	v_add_u32_e32 v36, 0x200, v36
	v_add_u32_e32 v38, 0x1000, v38
	s_or_b64 s[8:9], vcc, s[8:9]
	v_mov_b32_e32 v54, v32
	s_andn2_b64 exec, exec, s[8:9]
	s_mov_b32 s10, 0x2aaaaaab
	v_mul_hi_i32 v32, v54, s10
	v_lshrrev_b32_e32 v33, 31, v32
	v_ashrrev_i32_e32 v32, 2, v32
	v_add_u32_e32 v55, v32, v33
	v_add_u32_e32 v96, s15, v55
	s_movk_i32 s10, 0x80f
	v_cmp_lt_u32_e32 vcc, s10, v96
	s_and_saveexec_b64 s[10:11], vcc
	s_xor_b64 s[10:11], exec, s[10:11]
	s_movk_i32 s16, 0xff40
	v_mad_u64_u32 v[40:41], s[16:17], v55, s16, v[36:37]
	v_and_b32_e32 v41, 56, v40
	s_or_saveexec_b64 s[10:11], s[10:11]
	v_mov_b32_e32 v194, 0
	v_mov_b32_e32 v195, 0
	v_mov_b32_e32 v196, 0
	v_mov_b32_e32 v197, 0
	s_xor_b64 exec, exec, s[10:11]
	v_lshl_add_u64 v[32:33], s[6:7], 0, v[96:97]
	v_mov_b64_e32 v[34:35], s[56:57]
	v_mad_u64_u32 v[34:35], s[16:17], v32, s44, v[34:35]
	v_mov_b32_e32 v32, v35
	v_mad_u64_u32 v[32:33], s[16:17], v33, s44, v[32:33]
	s_movk_i32 s16, 0xfa00
	v_mov_b32_e32 v35, v32
	v_mad_u64_u32 v[32:33], s[16:17], v55, s16, v[38:39]
	v_and_b32_e32 v32, 0xfffffe00, v32
	s_movk_i32 s16, 0xff40
	v_ashrrev_i32_e32 v33, 31, v32
	v_mad_u64_u32 v[40:41], s[16:17], v55, s16, v[36:37]
	v_lshl_add_u64 v[32:33], v[32:33], 1, v[34:35]
	v_and_b32_e32 v41, 56, v40
	v_lshl_add_u64 v[32:33], v[32:33], 0, s[38:39]
	v_lshlrev_b32_e32 v96, 1, v41
	v_lshl_add_u64 v[32:33], v[32:33], 0, v[96:97]
	global_load_dwordx4 v[194:197], v[32:33], off
	s_or_b64 exec, exec, s[10:11]
	s_movk_i32 s10, 0x190
	v_mul_lo_u32 v55, v55, s10
	v_and_b32_e32 v40, 0x7fffffc0, v40
	v_add_u32_e32 v55, s76, v55
	v_lshlrev_b32_e32 v40, 1, v40
	v_lshlrev_b32_e32 v41, 1, v41
	v_add3_u32 v147, v55, v40, v41
	s_movk_i32 s10, 0x2d7
	v_add_u32_e32 v32, 64, v54
	v_cmp_lt_i32_e32 vcc, s10, v54
	v_add_u32_e32 v36, 0x200, v36
	v_add_u32_e32 v38, 0x1000, v38
	s_or_b64 s[8:9], vcc, s[8:9]
	v_mov_b32_e32 v54, v32
	s_andn2_b64 exec, exec, s[8:9]
	s_mov_b32 s10, 0x2aaaaaab
	v_mul_hi_i32 v32, v54, s10
	v_lshrrev_b32_e32 v33, 31, v32
	v_ashrrev_i32_e32 v32, 2, v32
	v_add_u32_e32 v55, v32, v33
	v_add_u32_e32 v96, s15, v55
	s_movk_i32 s10, 0x80f
	v_cmp_lt_u32_e32 vcc, s10, v96
	s_and_saveexec_b64 s[10:11], vcc
	s_xor_b64 s[10:11], exec, s[10:11]
	s_movk_i32 s16, 0xff40
	v_mad_u64_u32 v[40:41], s[16:17], v55, s16, v[36:37]
	v_and_b32_e32 v41, 56, v40
	s_or_saveexec_b64 s[10:11], s[10:11]
	v_mov_b32_e32 v198, 0
	v_mov_b32_e32 v199, 0
	v_mov_b32_e32 v200, 0
	v_mov_b32_e32 v201, 0
	s_xor_b64 exec, exec, s[10:11]
	v_lshl_add_u64 v[32:33], s[6:7], 0, v[96:97]
	v_mov_b64_e32 v[34:35], s[56:57]
	v_mad_u64_u32 v[34:35], s[16:17], v32, s44, v[34:35]
	v_mov_b32_e32 v32, v35
	v_mad_u64_u32 v[32:33], s[16:17], v33, s44, v[32:33]
	s_movk_i32 s16, 0xfa00
	v_mov_b32_e32 v35, v32
	v_mad_u64_u32 v[32:33], s[16:17], v55, s16, v[38:39]
	v_and_b32_e32 v32, 0xfffffe00, v32
	s_movk_i32 s16, 0xff40
	v_ashrrev_i32_e32 v33, 31, v32
	v_mad_u64_u32 v[40:41], s[16:17], v55, s16, v[36:37]
	v_lshl_add_u64 v[32:33], v[32:33], 1, v[34:35]
	v_and_b32_e32 v41, 56, v40
	v_lshl_add_u64 v[32:33], v[32:33], 0, s[38:39]
	v_lshlrev_b32_e32 v96, 1, v41
	v_lshl_add_u64 v[32:33], v[32:33], 0, v[96:97]
	global_load_dwordx4 v[198:201], v[32:33], off
	s_or_b64 exec, exec, s[10:11]
	s_movk_i32 s10, 0x190
	v_mul_lo_u32 v55, v55, s10
	v_and_b32_e32 v40, 0x7fffffc0, v40
	v_add_u32_e32 v55, s76, v55
	v_lshlrev_b32_e32 v40, 1, v40
	v_lshlrev_b32_e32 v41, 1, v41
	v_add3_u32 v148, v55, v40, v41
	s_movk_i32 s10, 0x2d7
	v_add_u32_e32 v32, 64, v54
	v_cmp_lt_i32_e32 vcc, s10, v54
	v_add_u32_e32 v36, 0x200, v36
	v_add_u32_e32 v38, 0x1000, v38
	s_or_b64 s[8:9], vcc, s[8:9]
	v_mov_b32_e32 v54, v32
	s_andn2_b64 exec, exec, s[8:9]
	s_mov_b32 s10, 0x2aaaaaab
	v_mul_hi_i32 v32, v54, s10
	v_lshrrev_b32_e32 v33, 31, v32
	v_ashrrev_i32_e32 v32, 2, v32
	v_add_u32_e32 v55, v32, v33
	v_add_u32_e32 v96, s15, v55
	s_movk_i32 s10, 0x80f
	v_cmp_lt_u32_e32 vcc, s10, v96
	s_and_saveexec_b64 s[10:11], vcc
	s_xor_b64 s[10:11], exec, s[10:11]
	s_movk_i32 s16, 0xff40
	v_mad_u64_u32 v[40:41], s[16:17], v55, s16, v[36:37]
	v_and_b32_e32 v41, 56, v40
	s_or_saveexec_b64 s[10:11], s[10:11]
	v_mov_b32_e32 v202, 0
	v_mov_b32_e32 v203, 0
	v_mov_b32_e32 v204, 0
	v_mov_b32_e32 v205, 0
	s_xor_b64 exec, exec, s[10:11]
	v_lshl_add_u64 v[32:33], s[6:7], 0, v[96:97]
	v_mov_b64_e32 v[34:35], s[56:57]
	v_mad_u64_u32 v[34:35], s[16:17], v32, s44, v[34:35]
	v_mov_b32_e32 v32, v35
	v_mad_u64_u32 v[32:33], s[16:17], v33, s44, v[32:33]
	s_movk_i32 s16, 0xfa00
	v_mov_b32_e32 v35, v32
	v_mad_u64_u32 v[32:33], s[16:17], v55, s16, v[38:39]
	v_and_b32_e32 v32, 0xfffffe00, v32
	s_movk_i32 s16, 0xff40
	v_ashrrev_i32_e32 v33, 31, v32
	v_mad_u64_u32 v[40:41], s[16:17], v55, s16, v[36:37]
	v_lshl_add_u64 v[32:33], v[32:33], 1, v[34:35]
	v_and_b32_e32 v41, 56, v40
	v_lshl_add_u64 v[32:33], v[32:33], 0, s[38:39]
	v_lshlrev_b32_e32 v96, 1, v41
	v_lshl_add_u64 v[32:33], v[32:33], 0, v[96:97]
	global_load_dwordx4 v[202:205], v[32:33], off
	s_or_b64 exec, exec, s[10:11]
	s_movk_i32 s10, 0x190
	v_mul_lo_u32 v55, v55, s10
	v_and_b32_e32 v40, 0x7fffffc0, v40
	v_add_u32_e32 v55, s76, v55
	v_lshlrev_b32_e32 v40, 1, v40
	v_lshlrev_b32_e32 v41, 1, v41
	v_add3_u32 v149, v55, v40, v41
	s_movk_i32 s10, 0x2d7
	v_add_u32_e32 v32, 64, v54
	v_cmp_lt_i32_e32 vcc, s10, v54
	v_add_u32_e32 v36, 0x200, v36
	v_add_u32_e32 v38, 0x1000, v38
	s_or_b64 s[8:9], vcc, s[8:9]
	v_mov_b32_e32 v54, v32
	s_andn2_b64 exec, exec, s[8:9]
	s_mov_b32 s10, 0x2aaaaaab
	v_mul_hi_i32 v32, v54, s10
	v_lshrrev_b32_e32 v33, 31, v32
	v_ashrrev_i32_e32 v32, 2, v32
	v_add_u32_e32 v55, v32, v33
	v_add_u32_e32 v96, s15, v55
	s_movk_i32 s10, 0x80f
	v_cmp_lt_u32_e32 vcc, s10, v96
	s_and_saveexec_b64 s[10:11], vcc
	s_xor_b64 s[10:11], exec, s[10:11]
	s_movk_i32 s16, 0xff40
	v_mad_u64_u32 v[40:41], s[16:17], v55, s16, v[36:37]
	v_and_b32_e32 v41, 56, v40
	s_or_saveexec_b64 s[10:11], s[10:11]
	v_mov_b32_e32 v206, 0
	v_mov_b32_e32 v207, 0
	v_mov_b32_e32 v208, 0
	v_mov_b32_e32 v209, 0
	s_xor_b64 exec, exec, s[10:11]
	v_lshl_add_u64 v[32:33], s[6:7], 0, v[96:97]
	v_mov_b64_e32 v[34:35], s[56:57]
	v_mad_u64_u32 v[34:35], s[16:17], v32, s44, v[34:35]
	v_mov_b32_e32 v32, v35
	v_mad_u64_u32 v[32:33], s[16:17], v33, s44, v[32:33]
	s_movk_i32 s16, 0xfa00
	v_mov_b32_e32 v35, v32
	v_mad_u64_u32 v[32:33], s[16:17], v55, s16, v[38:39]
	v_and_b32_e32 v32, 0xfffffe00, v32
	s_movk_i32 s16, 0xff40
	v_ashrrev_i32_e32 v33, 31, v32
	v_mad_u64_u32 v[40:41], s[16:17], v55, s16, v[36:37]
	v_lshl_add_u64 v[32:33], v[32:33], 1, v[34:35]
	v_and_b32_e32 v41, 56, v40
	v_lshl_add_u64 v[32:33], v[32:33], 0, s[38:39]
	v_lshlrev_b32_e32 v96, 1, v41
	v_lshl_add_u64 v[32:33], v[32:33], 0, v[96:97]
	global_load_dwordx4 v[206:209], v[32:33], off
	s_or_b64 exec, exec, s[10:11]
	s_movk_i32 s10, 0x190
	v_mul_lo_u32 v55, v55, s10
	v_and_b32_e32 v40, 0x7fffffc0, v40
	v_add_u32_e32 v55, s76, v55
	v_lshlrev_b32_e32 v40, 1, v40
	v_lshlrev_b32_e32 v41, 1, v41
	v_add3_u32 v150, v55, v40, v41
	s_movk_i32 s10, 0x2d7
	v_add_u32_e32 v32, 64, v54
	v_cmp_lt_i32_e32 vcc, s10, v54
	v_add_u32_e32 v36, 0x200, v36
	v_add_u32_e32 v38, 0x1000, v38
	s_or_b64 s[8:9], vcc, s[8:9]
	v_mov_b32_e32 v54, v32
	s_andn2_b64 exec, exec, s[8:9]
	s_mov_b32 s10, 0x2aaaaaab
	v_mul_hi_i32 v32, v54, s10
	v_lshrrev_b32_e32 v33, 31, v32
	v_ashrrev_i32_e32 v32, 2, v32
	v_add_u32_e32 v55, v32, v33
	v_add_u32_e32 v96, s15, v55
	s_movk_i32 s10, 0x80f
	v_cmp_lt_u32_e32 vcc, s10, v96
	s_and_saveexec_b64 s[10:11], vcc
	s_xor_b64 s[10:11], exec, s[10:11]
	s_movk_i32 s16, 0xff40
	v_mad_u64_u32 v[40:41], s[16:17], v55, s16, v[36:37]
	v_and_b32_e32 v41, 56, v40
	s_or_saveexec_b64 s[10:11], s[10:11]
	v_mov_b32_e32 v210, 0
	v_mov_b32_e32 v211, 0
	v_mov_b32_e32 v212, 0
	v_mov_b32_e32 v213, 0
	s_xor_b64 exec, exec, s[10:11]
	v_lshl_add_u64 v[32:33], s[6:7], 0, v[96:97]
	v_mov_b64_e32 v[34:35], s[56:57]
	v_mad_u64_u32 v[34:35], s[16:17], v32, s44, v[34:35]
	v_mov_b32_e32 v32, v35
	v_mad_u64_u32 v[32:33], s[16:17], v33, s44, v[32:33]
	s_movk_i32 s16, 0xfa00
	v_mov_b32_e32 v35, v32
	v_mad_u64_u32 v[32:33], s[16:17], v55, s16, v[38:39]
	v_and_b32_e32 v32, 0xfffffe00, v32
	s_movk_i32 s16, 0xff40
	v_ashrrev_i32_e32 v33, 31, v32
	v_mad_u64_u32 v[40:41], s[16:17], v55, s16, v[36:37]
	v_lshl_add_u64 v[32:33], v[32:33], 1, v[34:35]
	v_and_b32_e32 v41, 56, v40
	v_lshl_add_u64 v[32:33], v[32:33], 0, s[38:39]
	v_lshlrev_b32_e32 v96, 1, v41
	v_lshl_add_u64 v[32:33], v[32:33], 0, v[96:97]
	global_load_dwordx4 v[210:213], v[32:33], off
	s_or_b64 exec, exec, s[10:11]
	s_movk_i32 s10, 0x190
	v_mul_lo_u32 v55, v55, s10
	v_and_b32_e32 v40, 0x7fffffc0, v40
	v_add_u32_e32 v55, s76, v55
	v_lshlrev_b32_e32 v40, 1, v40
	v_lshlrev_b32_e32 v41, 1, v41
	v_add3_u32 v151, v55, v40, v41
	s_movk_i32 s10, 0x2d7
	s_mov_b64 s[100:101], exec
	v_add_u32_e32 v32, 64, v54
	v_cmp_lt_i32_e32 vcc, s10, v54
	v_add_u32_e32 v36, 0x200, v36
	v_add_u32_e32 v38, 0x1000, v38
	s_or_b64 s[8:9], vcc, s[8:9]
	v_mov_b32_e32 v54, v32
	s_andn2_b64 exec, exec, s[8:9]
	s_waitcnt vmcnt(0)
	s_mov_b64 exec, s[98:99]
	ds_write_b128 v139, v[162:165]
	ds_write_b128 v140, v[166:169]
	ds_write_b128 v141, v[170:173]
	ds_write_b128 v142, v[174:177]
	ds_write_b128 v143, v[178:181]
	ds_write_b128 v144, v[182:185]
	ds_write_b128 v145, v[186:189]
	ds_write_b128 v146, v[190:193]
	ds_write_b128 v147, v[194:197]
	ds_write_b128 v148, v[198:201]
	ds_write_b128 v149, v[202:205]
	ds_write_b128 v150, v[206:209]
	s_mov_b64 exec, s[100:101]
	ds_write_b128 v151, v[210:213]
